# bisection passes: the per-lane count starts from the zero register in the first carry add (one vector move per pass removed)
# speedup vs baseline: 1.0058x; 1.0058x over previous
; template <int NB>
; __device__ __forceinline__ void bisect256(const unsigned (&x)[64], unsigned& tau_out, int& cge_out) {
;     ...
;     const unsigned cand = tau | (1u << bit);
;     unsigned cl = 0u;
; #pragma unroll
;     for (int blk = 0; blk < NB; ++blk) {
;       unsigned long long m0, m1, m2, m3, m4, m5, m6, m7;
;       asm volatile(
;           "v_cmp_ge_u32_e64 %1, %9, %17\n\tv_cmp_ge_u32_e64 %2, %10, %17\n\tv_cmp_ge_u32_e64 %3, %11, %17\n\tv_cmp_ge_u32_e64 %4, %12, %17\n\t"
;           "v_cmp_ge_u32_e64 %5, %13, %17\n\tv_cmp_ge_u32_e64 %6, %14, %17\n\tv_cmp_ge_u32_e64 %7, %15, %17\n\tv_cmp_ge_u32_e64 %8, %16, %17\n\t"
;           "v_addc_co_u32_e64 %0, %1, 0, %0, %1\n\tv_addc_co_u32_e64 %0, %2, 0, %0, %2\n\tv_addc_co_u32_e64 %0, %3, 0, %0, %3\n\t"
;           "v_addc_co_u32_e64 %0, %4, 0, %0, %4\n\tv_addc_co_u32_e64 %0, %5, 0, %0, %5\n\tv_addc_co_u32_e64 %0, %6, 0, %0, %6\n\t"
;           "v_addc_co_u32_e64 %0, %7, 0, %0, %7\n\tv_addc_co_u32_e64 %0, %8, 0, %0, %8"
;           : "+v"(cl), "=&s"(m0), "=&s"(m1), "=&s"(m2), "=&s"(m3), "=&s"(m4), "=&s"(m5), "=&s"(m6), "=&s"(m7)
;           : "v"(x[blk * 8 + 0]), "v"(x[blk * 8 + 1]), "v"(x[blk * 8 + 2]), "v"(x[blk * 8 + 3]), "v"(x[blk * 8 + 4]), "v"(x[blk * 8 + 5]),
;             "v"(x[blk * 8 + 6]), "v"(x[blk * 8 + 7]), "v"(cand));
;     }
;     cl += (unsigned)__builtin_amdgcn_update_dpp(0, (int)cl, 0x111, 0xf, 0xf, true);
;     cl += (unsigned)__builtin_amdgcn_update_dpp(0, (int)cl, 0x112, 0xf, 0xf, true);
;     cl += (unsigned)__builtin_amdgcn_update_dpp(0, (int)cl, 0x114, 0xf, 0xf, true);
;     cl += (unsigned)__builtin_amdgcn_update_dpp(0, (int)cl, 0x118, 0xf, 0xf, true);
;     const int cnt = __builtin_amdgcn_readlane((int)cl, 15) + __builtin_amdgcn_readlane((int)cl, 31) + __builtin_amdgcn_readlane((int)cl, 47) +
;                     __builtin_amdgcn_readlane((int)cl, 63);
;     if (cnt >= 256) { tau = cand; cge = cnt; }
;     if (cnt == 256) break;
;   }
.Lselq0_top:
	s_or_b32 vcc_lo, s101, vcc_hi
	v_cmp_ge_u32_e64 s[38:39], v239, vcc_lo
	v_cmp_ge_u32_e64 s[42:43], v238, vcc_lo
	v_cmp_ge_u32_e64 s[62:63], v237, vcc_lo
	v_cmp_ge_u32_e64 s[64:65], v236, vcc_lo
	v_cmp_ge_u32_e64 s[66:67], v235, vcc_lo
	v_cmp_ge_u32_e64 s[68:69], v234, vcc_lo
	v_cmp_ge_u32_e64 s[70:71], v233, vcc_lo
	v_cmp_ge_u32_e64 s[72:73], v231, vcc_lo
	v_addc_co_u32_e64 v242, s[38:39], 0, v17, s[38:39]
	v_addc_co_u32_e64 v242, s[42:43], 0, v242, s[42:43]
	v_addc_co_u32_e64 v242, s[62:63], 0, v242, s[62:63]
	v_addc_co_u32_e64 v242, s[64:65], 0, v242, s[64:65]
	v_addc_co_u32_e64 v242, s[66:67], 0, v242, s[66:67]
	v_addc_co_u32_e64 v242, s[68:69], 0, v242, s[68:69]
	v_addc_co_u32_e64 v242, s[70:71], 0, v242, s[70:71]
	v_addc_co_u32_e64 v242, s[72:73], 0, v242, s[72:73]
	v_cmp_ge_u32_e64 s[38:39], v232, vcc_lo
	v_cmp_ge_u32_e64 s[42:43], v230, vcc_lo
	v_cmp_ge_u32_e64 s[62:63], v229, vcc_lo
	v_cmp_ge_u32_e64 s[64:65], v228, vcc_lo
	v_cmp_ge_u32_e64 s[66:67], v227, vcc_lo
	v_cmp_ge_u32_e64 s[68:69], v226, vcc_lo
	v_cmp_ge_u32_e64 s[70:71], v225, vcc_lo
	v_cmp_ge_u32_e64 s[72:73], v223, vcc_lo
	v_addc_co_u32_e64 v242, s[38:39], 0, v242, s[38:39]
	v_addc_co_u32_e64 v242, s[42:43], 0, v242, s[42:43]
	v_addc_co_u32_e64 v242, s[62:63], 0, v242, s[62:63]
	v_addc_co_u32_e64 v242, s[64:65], 0, v242, s[64:65]
	v_addc_co_u32_e64 v242, s[66:67], 0, v242, s[66:67]
	v_addc_co_u32_e64 v242, s[68:69], 0, v242, s[68:69]
	v_addc_co_u32_e64 v242, s[70:71], 0, v242, s[70:71]
	v_addc_co_u32_e64 v242, s[72:73], 0, v242, s[72:73]
	v_cmp_ge_u32_e64 s[38:39], v224, vcc_lo
	v_cmp_ge_u32_e64 s[42:43], v222, vcc_lo
	v_cmp_ge_u32_e64 s[62:63], v221, vcc_lo
	v_cmp_ge_u32_e64 s[64:65], v220, vcc_lo
	v_cmp_ge_u32_e64 s[66:67], v219, vcc_lo
	v_cmp_ge_u32_e64 s[68:69], v218, vcc_lo
	v_cmp_ge_u32_e64 s[70:71], v217, vcc_lo
	v_cmp_ge_u32_e64 s[72:73], v215, vcc_lo
	v_addc_co_u32_e64 v242, s[38:39], 0, v242, s[38:39]
	v_addc_co_u32_e64 v242, s[42:43], 0, v242, s[42:43]
	v_addc_co_u32_e64 v242, s[62:63], 0, v242, s[62:63]
	v_addc_co_u32_e64 v242, s[64:65], 0, v242, s[64:65]
	v_addc_co_u32_e64 v242, s[66:67], 0, v242, s[66:67]
	v_addc_co_u32_e64 v242, s[68:69], 0, v242, s[68:69]
	v_addc_co_u32_e64 v242, s[70:71], 0, v242, s[70:71]
	v_addc_co_u32_e64 v242, s[72:73], 0, v242, s[72:73]
	v_cmp_ge_u32_e64 s[38:39], v216, vcc_lo
	v_cmp_ge_u32_e64 s[42:43], v214, vcc_lo
	v_cmp_ge_u32_e64 s[62:63], v213, vcc_lo
	v_cmp_ge_u32_e64 s[64:65], v212, vcc_lo
	v_cmp_ge_u32_e64 s[66:67], v211, vcc_lo
	v_cmp_ge_u32_e64 s[68:69], v210, vcc_lo
	v_cmp_ge_u32_e64 s[70:71], v207, vcc_lo
	v_cmp_ge_u32_e64 s[72:73], v194, vcc_lo
	v_addc_co_u32_e64 v242, s[38:39], 0, v242, s[38:39]
	v_addc_co_u32_e64 v242, s[42:43], 0, v242, s[42:43]
	v_addc_co_u32_e64 v242, s[62:63], 0, v242, s[62:63]
	v_addc_co_u32_e64 v242, s[64:65], 0, v242, s[64:65]
	v_addc_co_u32_e64 v242, s[66:67], 0, v242, s[66:67]
	v_addc_co_u32_e64 v242, s[68:69], 0, v242, s[68:69]
	v_addc_co_u32_e64 v242, s[70:71], 0, v242, s[70:71]
	v_addc_co_u32_e64 v242, s[72:73], 0, v242, s[72:73]
	v_cmp_ge_u32_e64 s[38:39], v195, vcc_lo
	v_cmp_ge_u32_e64 s[42:43], v193, vcc_lo
	v_cmp_ge_u32_e64 s[62:63], v192, vcc_lo
	v_cmp_ge_u32_e64 s[64:65], v191, vcc_lo
	v_cmp_ge_u32_e64 s[66:67], v190, vcc_lo
	v_cmp_ge_u32_e64 s[68:69], v189, vcc_lo
	v_cmp_ge_u32_e64 s[70:71], v188, vcc_lo
	v_cmp_ge_u32_e64 s[72:73], v186, vcc_lo
	v_addc_co_u32_e64 v242, s[38:39], 0, v242, s[38:39]
	v_addc_co_u32_e64 v242, s[42:43], 0, v242, s[42:43]
	v_addc_co_u32_e64 v242, s[62:63], 0, v242, s[62:63]
	v_addc_co_u32_e64 v242, s[64:65], 0, v242, s[64:65]
	v_addc_co_u32_e64 v242, s[66:67], 0, v242, s[66:67]
	v_addc_co_u32_e64 v242, s[68:69], 0, v242, s[68:69]
	v_addc_co_u32_e64 v242, s[70:71], 0, v242, s[70:71]
	v_addc_co_u32_e64 v242, s[72:73], 0, v242, s[72:73]
	v_cmp_ge_u32_e64 s[38:39], v187, vcc_lo
	v_cmp_ge_u32_e64 s[42:43], v185, vcc_lo
	v_cmp_ge_u32_e64 s[62:63], v184, vcc_lo
	v_cmp_ge_u32_e64 s[64:65], v183, vcc_lo
	v_cmp_ge_u32_e64 s[66:67], v182, vcc_lo
	v_cmp_ge_u32_e64 s[68:69], v181, vcc_lo
	v_cmp_ge_u32_e64 s[70:71], v180, vcc_lo
	v_cmp_ge_u32_e64 s[72:73], v178, vcc_lo
	v_addc_co_u32_e64 v242, s[38:39], 0, v242, s[38:39]
	v_addc_co_u32_e64 v242, s[42:43], 0, v242, s[42:43]
	v_addc_co_u32_e64 v242, s[62:63], 0, v242, s[62:63]
	v_addc_co_u32_e64 v242, s[64:65], 0, v242, s[64:65]
	v_addc_co_u32_e64 v242, s[66:67], 0, v242, s[66:67]
	v_addc_co_u32_e64 v242, s[68:69], 0, v242, s[68:69]
	v_addc_co_u32_e64 v242, s[70:71], 0, v242, s[70:71]
	v_addc_co_u32_e64 v242, s[72:73], 0, v242, s[72:73]
	v_cmp_ge_u32_e64 s[38:39], v179, vcc_lo
	v_cmp_ge_u32_e64 s[42:43], v177, vcc_lo
	v_cmp_ge_u32_e64 s[62:63], v176, vcc_lo
	v_cmp_ge_u32_e64 s[64:65], v175, vcc_lo
	v_cmp_ge_u32_e64 s[66:67], v174, vcc_lo
	v_cmp_ge_u32_e64 s[68:69], v173, vcc_lo
	v_cmp_ge_u32_e64 s[70:71], v172, vcc_lo
	v_cmp_ge_u32_e64 s[72:73], v115, vcc_lo
	v_addc_co_u32_e64 v242, s[38:39], 0, v242, s[38:39]
	v_addc_co_u32_e64 v242, s[42:43], 0, v242, s[42:43]
	v_addc_co_u32_e64 v242, s[62:63], 0, v242, s[62:63]
	v_addc_co_u32_e64 v242, s[64:65], 0, v242, s[64:65]
	v_addc_co_u32_e64 v242, s[66:67], 0, v242, s[66:67]
	v_addc_co_u32_e64 v242, s[68:69], 0, v242, s[68:69]
	v_addc_co_u32_e64 v242, s[70:71], 0, v242, s[70:71]
	v_addc_co_u32_e64 v242, s[72:73], 0, v242, s[72:73]
	s_nop 1
	v_add_u32_dpp v242, v242, v242 row_shr:1 row_mask:0xf bank_mask:0xf bound_ctrl:1
	s_nop 1
	v_add_u32_dpp v242, v242, v242 row_shr:2 row_mask:0xf bank_mask:0xf bound_ctrl:1
	s_nop 1
	v_add_u32_dpp v242, v242, v242 row_shr:4 row_mask:0xf bank_mask:0xf bound_ctrl:1
	s_nop 1
	v_add_u32_dpp v242, v242, v242 row_shr:8 row_mask:0xf bank_mask:0xf bound_ctrl:1
	s_nop 0
	v_readlane_b32 s38, v242, 15
	v_readlane_b32 s39, v242, 31
	s_add_i32 s38, s39, s38
	v_readlane_b32 s39, v242, 47
	s_add_i32 s38, s38, s39
	v_readlane_b32 s39, v242, 63
	s_add_i32 s38, s38, s39
	s_cmpk_gt_i32 s38, 0xff
	s_cselect_b32 s59, s38, s59
	s_cselect_b32 s101, vcc_lo, s101
	s_cmpk_eq_i32 s38, 0x100
	s_cbranch_scc1 .Lselq0_exit
	s_lshr_b32 vcc_hi, vcc_hi, 1
	s_cmp_lg_u32 vcc_hi, 0
	s_cbranch_scc1 .Lselq0_top

; template <int NB>
; __device__ __forceinline__ void bisect256(const unsigned (&x)[64], unsigned& tau_out, int& cge_out) {
;     ...
;     const unsigned cand = tau | (1u << bit);
;     unsigned cl = 0u;
; #pragma unroll
;     for (int blk = 0; blk < NB; ++blk) {
;       unsigned long long m0, m1, m2, m3, m4, m5, m6, m7;
;       asm volatile(
;           "v_cmp_ge_u32_e64 %1, %9, %17\n\tv_cmp_ge_u32_e64 %2, %10, %17\n\tv_cmp_ge_u32_e64 %3, %11, %17\n\tv_cmp_ge_u32_e64 %4, %12, %17\n\t"
;           "v_cmp_ge_u32_e64 %5, %13, %17\n\tv_cmp_ge_u32_e64 %6, %14, %17\n\tv_cmp_ge_u32_e64 %7, %15, %17\n\tv_cmp_ge_u32_e64 %8, %16, %17\n\t"
;           "v_addc_co_u32_e64 %0, %1, 0, %0, %1\n\tv_addc_co_u32_e64 %0, %2, 0, %0, %2\n\tv_addc_co_u32_e64 %0, %3, 0, %0, %3\n\t"
;           "v_addc_co_u32_e64 %0, %4, 0, %0, %4\n\tv_addc_co_u32_e64 %0, %5, 0, %0, %5\n\tv_addc_co_u32_e64 %0, %6, 0, %0, %6\n\t"
;           "v_addc_co_u32_e64 %0, %7, 0, %0, %7\n\tv_addc_co_u32_e64 %0, %8, 0, %0, %8"
;           : "+v"(cl), "=&s"(m0), "=&s"(m1), "=&s"(m2), "=&s"(m3), "=&s"(m4), "=&s"(m5), "=&s"(m6), "=&s"(m7)
;           : "v"(x[blk * 8 + 0]), "v"(x[blk * 8 + 1]), "v"(x[blk * 8 + 2]), "v"(x[blk * 8 + 3]), "v"(x[blk * 8 + 4]), "v"(x[blk * 8 + 5]),
;             "v"(x[blk * 8 + 6]), "v"(x[blk * 8 + 7]), "v"(cand));
;     }
;     cl += (unsigned)__builtin_amdgcn_update_dpp(0, (int)cl, 0x111, 0xf, 0xf, true);
;     cl += (unsigned)__builtin_amdgcn_update_dpp(0, (int)cl, 0x112, 0xf, 0xf, true);
;     cl += (unsigned)__builtin_amdgcn_update_dpp(0, (int)cl, 0x114, 0xf, 0xf, true);
;     cl += (unsigned)__builtin_amdgcn_update_dpp(0, (int)cl, 0x118, 0xf, 0xf, true);
;     const int cnt = __builtin_amdgcn_readlane((int)cl, 15) + __builtin_amdgcn_readlane((int)cl, 31) + __builtin_amdgcn_readlane((int)cl, 47) +
;                     __builtin_amdgcn_readlane((int)cl, 63);
;     if (cnt >= 256) { tau = cand; cge = cnt; }
;     if (cnt == 256) break;
;   }
.Lselq1_top:
	s_or_b32 vcc_lo, s101, vcc_hi
	v_cmp_ge_u32_e64 s[42:43], v239, vcc_lo
	v_cmp_ge_u32_e64 s[62:63], v238, vcc_lo
	v_cmp_ge_u32_e64 s[64:65], v237, vcc_lo
	v_cmp_ge_u32_e64 s[66:67], v236, vcc_lo
	v_cmp_ge_u32_e64 s[68:69], v235, vcc_lo
	v_cmp_ge_u32_e64 s[70:71], v234, vcc_lo
	v_cmp_ge_u32_e64 s[72:73], v233, vcc_lo
	v_cmp_ge_u32_e64 s[74:75], v231, vcc_lo
	v_addc_co_u32_e64 v242, s[42:43], 0, v17, s[42:43]
	v_addc_co_u32_e64 v242, s[62:63], 0, v242, s[62:63]
	v_addc_co_u32_e64 v242, s[64:65], 0, v242, s[64:65]
	v_addc_co_u32_e64 v242, s[66:67], 0, v242, s[66:67]
	v_addc_co_u32_e64 v242, s[68:69], 0, v242, s[68:69]
	v_addc_co_u32_e64 v242, s[70:71], 0, v242, s[70:71]
	v_addc_co_u32_e64 v242, s[72:73], 0, v242, s[72:73]
	v_addc_co_u32_e64 v242, s[74:75], 0, v242, s[74:75]
	v_cmp_ge_u32_e64 s[42:43], v232, vcc_lo
	v_cmp_ge_u32_e64 s[62:63], v230, vcc_lo
	v_cmp_ge_u32_e64 s[64:65], v229, vcc_lo
	v_cmp_ge_u32_e64 s[66:67], v228, vcc_lo
	v_cmp_ge_u32_e64 s[68:69], v227, vcc_lo
	v_cmp_ge_u32_e64 s[70:71], v226, vcc_lo
	v_cmp_ge_u32_e64 s[72:73], v225, vcc_lo
	v_cmp_ge_u32_e64 s[74:75], v223, vcc_lo
	v_addc_co_u32_e64 v242, s[42:43], 0, v242, s[42:43]
	v_addc_co_u32_e64 v242, s[62:63], 0, v242, s[62:63]
	v_addc_co_u32_e64 v242, s[64:65], 0, v242, s[64:65]
	v_addc_co_u32_e64 v242, s[66:67], 0, v242, s[66:67]
	v_addc_co_u32_e64 v242, s[68:69], 0, v242, s[68:69]
	v_addc_co_u32_e64 v242, s[70:71], 0, v242, s[70:71]
	v_addc_co_u32_e64 v242, s[72:73], 0, v242, s[72:73]
	v_addc_co_u32_e64 v242, s[74:75], 0, v242, s[74:75]
	v_cmp_ge_u32_e64 s[42:43], v224, vcc_lo
	v_cmp_ge_u32_e64 s[62:63], v222, vcc_lo
	v_cmp_ge_u32_e64 s[64:65], v221, vcc_lo
	v_cmp_ge_u32_e64 s[66:67], v220, vcc_lo
	v_cmp_ge_u32_e64 s[68:69], v219, vcc_lo
	v_cmp_ge_u32_e64 s[70:71], v218, vcc_lo
	v_cmp_ge_u32_e64 s[72:73], v217, vcc_lo
	v_cmp_ge_u32_e64 s[74:75], v215, vcc_lo
	v_addc_co_u32_e64 v242, s[42:43], 0, v242, s[42:43]
	v_addc_co_u32_e64 v242, s[62:63], 0, v242, s[62:63]
	v_addc_co_u32_e64 v242, s[64:65], 0, v242, s[64:65]
	v_addc_co_u32_e64 v242, s[66:67], 0, v242, s[66:67]
	v_addc_co_u32_e64 v242, s[68:69], 0, v242, s[68:69]
	v_addc_co_u32_e64 v242, s[70:71], 0, v242, s[70:71]
	v_addc_co_u32_e64 v242, s[72:73], 0, v242, s[72:73]
	v_addc_co_u32_e64 v242, s[74:75], 0, v242, s[74:75]
	v_cmp_ge_u32_e64 s[42:43], v216, vcc_lo
	v_cmp_ge_u32_e64 s[62:63], v214, vcc_lo
	v_cmp_ge_u32_e64 s[64:65], v213, vcc_lo
	v_cmp_ge_u32_e64 s[66:67], v212, vcc_lo
	v_cmp_ge_u32_e64 s[68:69], v211, vcc_lo
	v_cmp_ge_u32_e64 s[70:71], v210, vcc_lo
	v_cmp_ge_u32_e64 s[72:73], v207, vcc_lo
	v_cmp_ge_u32_e64 s[74:75], v194, vcc_lo
	v_addc_co_u32_e64 v242, s[42:43], 0, v242, s[42:43]
	v_addc_co_u32_e64 v242, s[62:63], 0, v242, s[62:63]
	v_addc_co_u32_e64 v242, s[64:65], 0, v242, s[64:65]
	v_addc_co_u32_e64 v242, s[66:67], 0, v242, s[66:67]
	v_addc_co_u32_e64 v242, s[68:69], 0, v242, s[68:69]
	v_addc_co_u32_e64 v242, s[70:71], 0, v242, s[70:71]
	v_addc_co_u32_e64 v242, s[72:73], 0, v242, s[72:73]
	v_addc_co_u32_e64 v242, s[74:75], 0, v242, s[74:75]
	v_cmp_ge_u32_e64 s[42:43], v195, vcc_lo
	v_cmp_ge_u32_e64 s[62:63], v193, vcc_lo
	v_cmp_ge_u32_e64 s[64:65], v192, vcc_lo
	v_cmp_ge_u32_e64 s[66:67], v191, vcc_lo
	v_cmp_ge_u32_e64 s[68:69], v190, vcc_lo
	v_cmp_ge_u32_e64 s[70:71], v189, vcc_lo
	v_cmp_ge_u32_e64 s[72:73], v188, vcc_lo
	v_cmp_ge_u32_e64 s[74:75], v186, vcc_lo
	v_addc_co_u32_e64 v242, s[42:43], 0, v242, s[42:43]
	v_addc_co_u32_e64 v242, s[62:63], 0, v242, s[62:63]
	v_addc_co_u32_e64 v242, s[64:65], 0, v242, s[64:65]
	v_addc_co_u32_e64 v242, s[66:67], 0, v242, s[66:67]
	v_addc_co_u32_e64 v242, s[68:69], 0, v242, s[68:69]
	v_addc_co_u32_e64 v242, s[70:71], 0, v242, s[70:71]
	v_addc_co_u32_e64 v242, s[72:73], 0, v242, s[72:73]
	v_addc_co_u32_e64 v242, s[74:75], 0, v242, s[74:75]
	v_cmp_ge_u32_e64 s[42:43], v187, vcc_lo
	v_cmp_ge_u32_e64 s[62:63], v185, vcc_lo
	v_cmp_ge_u32_e64 s[64:65], v184, vcc_lo
	v_cmp_ge_u32_e64 s[66:67], v183, vcc_lo
	v_cmp_ge_u32_e64 s[68:69], v182, vcc_lo
	v_cmp_ge_u32_e64 s[70:71], v181, vcc_lo
	v_cmp_ge_u32_e64 s[72:73], v180, vcc_lo
	v_cmp_ge_u32_e64 s[74:75], v178, vcc_lo
	v_addc_co_u32_e64 v242, s[42:43], 0, v242, s[42:43]
	v_addc_co_u32_e64 v242, s[62:63], 0, v242, s[62:63]
	v_addc_co_u32_e64 v242, s[64:65], 0, v242, s[64:65]
	v_addc_co_u32_e64 v242, s[66:67], 0, v242, s[66:67]
	v_addc_co_u32_e64 v242, s[68:69], 0, v242, s[68:69]
	v_addc_co_u32_e64 v242, s[70:71], 0, v242, s[70:71]
	v_addc_co_u32_e64 v242, s[72:73], 0, v242, s[72:73]
	v_addc_co_u32_e64 v242, s[74:75], 0, v242, s[74:75]
	s_nop 1
	v_add_u32_dpp v242, v242, v242 row_shr:1 row_mask:0xf bank_mask:0xf bound_ctrl:1
	s_nop 1
	v_add_u32_dpp v242, v242, v242 row_shr:2 row_mask:0xf bank_mask:0xf bound_ctrl:1
	s_nop 1
	v_add_u32_dpp v242, v242, v242 row_shr:4 row_mask:0xf bank_mask:0xf bound_ctrl:1
	s_nop 1
	v_add_u32_dpp v242, v242, v242 row_shr:8 row_mask:0xf bank_mask:0xf bound_ctrl:1
	s_nop 0
	v_readlane_b32 s42, v242, 15
	v_readlane_b32 s43, v242, 31
	s_add_i32 s42, s43, s42
	v_readlane_b32 s43, v242, 47
	s_add_i32 s42, s42, s43
	v_readlane_b32 s43, v242, 63
	s_add_i32 s42, s42, s43
	s_cmpk_gt_i32 s42, 0xff
	s_cselect_b32 s59, s42, s59
	s_cselect_b32 s101, vcc_lo, s101
	s_cmpk_eq_i32 s42, 0x100
	s_cbranch_scc1 .Lselq1_exit
	s_lshr_b32 vcc_hi, vcc_hi, 1
	s_cmp_lg_u32 vcc_hi, 0
	s_cbranch_scc1 .Lselq1_top

; template <int NB>
; __device__ __forceinline__ void bisect256(const unsigned (&x)[64], unsigned& tau_out, int& cge_out) {
;     ...
;     const unsigned cand = tau | (1u << bit);
;     unsigned cl = 0u;
; #pragma unroll
;     for (int blk = 0; blk < NB; ++blk) {
;       unsigned long long m0, m1, m2, m3, m4, m5, m6, m7;
;       asm volatile(
;           "v_cmp_ge_u32_e64 %1, %9, %17\n\tv_cmp_ge_u32_e64 %2, %10, %17\n\tv_cmp_ge_u32_e64 %3, %11, %17\n\tv_cmp_ge_u32_e64 %4, %12, %17\n\t"
;           "v_cmp_ge_u32_e64 %5, %13, %17\n\tv_cmp_ge_u32_e64 %6, %14, %17\n\tv_cmp_ge_u32_e64 %7, %15, %17\n\tv_cmp_ge_u32_e64 %8, %16, %17\n\t"
;           "v_addc_co_u32_e64 %0, %1, 0, %0, %1\n\tv_addc_co_u32_e64 %0, %2, 0, %0, %2\n\tv_addc_co_u32_e64 %0, %3, 0, %0, %3\n\t"
;           "v_addc_co_u32_e64 %0, %4, 0, %0, %4\n\tv_addc_co_u32_e64 %0, %5, 0, %0, %5\n\tv_addc_co_u32_e64 %0, %6, 0, %0, %6\n\t"
;           "v_addc_co_u32_e64 %0, %7, 0, %0, %7\n\tv_addc_co_u32_e64 %0, %8, 0, %0, %8"
;           : "+v"(cl), "=&s"(m0), "=&s"(m1), "=&s"(m2), "=&s"(m3), "=&s"(m4), "=&s"(m5), "=&s"(m6), "=&s"(m7)
;           : "v"(x[blk * 8 + 0]), "v"(x[blk * 8 + 1]), "v"(x[blk * 8 + 2]), "v"(x[blk * 8 + 3]), "v"(x[blk * 8 + 4]), "v"(x[blk * 8 + 5]),
;             "v"(x[blk * 8 + 6]), "v"(x[blk * 8 + 7]), "v"(cand));
;     }
;     cl += (unsigned)__builtin_amdgcn_update_dpp(0, (int)cl, 0x111, 0xf, 0xf, true);
;     cl += (unsigned)__builtin_amdgcn_update_dpp(0, (int)cl, 0x112, 0xf, 0xf, true);
;     cl += (unsigned)__builtin_amdgcn_update_dpp(0, (int)cl, 0x114, 0xf, 0xf, true);
;     cl += (unsigned)__builtin_amdgcn_update_dpp(0, (int)cl, 0x118, 0xf, 0xf, true);
;     const int cnt = __builtin_amdgcn_readlane((int)cl, 15) + __builtin_amdgcn_readlane((int)cl, 31) + __builtin_amdgcn_readlane((int)cl, 47) +
;                     __builtin_amdgcn_readlane((int)cl, 63);
;     if (cnt >= 256) { tau = cand; cge = cnt; }
;     if (cnt == 256) break;
;   }
.Lselq2_top:
	s_or_b32 vcc_lo, s101, vcc_hi
	v_cmp_ge_u32_e64 s[42:43], v239, vcc_lo
	v_cmp_ge_u32_e64 s[62:63], v238, vcc_lo
	v_cmp_ge_u32_e64 s[64:65], v237, vcc_lo
	v_cmp_ge_u32_e64 s[66:67], v236, vcc_lo
	v_cmp_ge_u32_e64 s[68:69], v235, vcc_lo
	v_cmp_ge_u32_e64 s[70:71], v234, vcc_lo
	v_cmp_ge_u32_e64 s[72:73], v233, vcc_lo
	v_cmp_ge_u32_e64 s[74:75], v231, vcc_lo
	v_addc_co_u32_e64 v242, s[42:43], 0, v17, s[42:43]
	v_addc_co_u32_e64 v242, s[62:63], 0, v242, s[62:63]
	v_addc_co_u32_e64 v242, s[64:65], 0, v242, s[64:65]
	v_addc_co_u32_e64 v242, s[66:67], 0, v242, s[66:67]
	v_addc_co_u32_e64 v242, s[68:69], 0, v242, s[68:69]
	v_addc_co_u32_e64 v242, s[70:71], 0, v242, s[70:71]
	v_addc_co_u32_e64 v242, s[72:73], 0, v242, s[72:73]
	v_addc_co_u32_e64 v242, s[74:75], 0, v242, s[74:75]
	v_cmp_ge_u32_e64 s[42:43], v232, vcc_lo
	v_cmp_ge_u32_e64 s[62:63], v230, vcc_lo
	v_cmp_ge_u32_e64 s[64:65], v229, vcc_lo
	v_cmp_ge_u32_e64 s[66:67], v228, vcc_lo
	v_cmp_ge_u32_e64 s[68:69], v227, vcc_lo
	v_cmp_ge_u32_e64 s[70:71], v226, vcc_lo
	v_cmp_ge_u32_e64 s[72:73], v225, vcc_lo
	v_cmp_ge_u32_e64 s[74:75], v223, vcc_lo
	v_addc_co_u32_e64 v242, s[42:43], 0, v242, s[42:43]
	v_addc_co_u32_e64 v242, s[62:63], 0, v242, s[62:63]
	v_addc_co_u32_e64 v242, s[64:65], 0, v242, s[64:65]
	v_addc_co_u32_e64 v242, s[66:67], 0, v242, s[66:67]
	v_addc_co_u32_e64 v242, s[68:69], 0, v242, s[68:69]
	v_addc_co_u32_e64 v242, s[70:71], 0, v242, s[70:71]
	v_addc_co_u32_e64 v242, s[72:73], 0, v242, s[72:73]
	v_addc_co_u32_e64 v242, s[74:75], 0, v242, s[74:75]
	v_cmp_ge_u32_e64 s[42:43], v224, vcc_lo
	v_cmp_ge_u32_e64 s[62:63], v222, vcc_lo
	v_cmp_ge_u32_e64 s[64:65], v221, vcc_lo
	v_cmp_ge_u32_e64 s[66:67], v220, vcc_lo
	v_cmp_ge_u32_e64 s[68:69], v219, vcc_lo
	v_cmp_ge_u32_e64 s[70:71], v218, vcc_lo
	v_cmp_ge_u32_e64 s[72:73], v217, vcc_lo
	v_cmp_ge_u32_e64 s[74:75], v215, vcc_lo
	v_addc_co_u32_e64 v242, s[42:43], 0, v242, s[42:43]
	v_addc_co_u32_e64 v242, s[62:63], 0, v242, s[62:63]
	v_addc_co_u32_e64 v242, s[64:65], 0, v242, s[64:65]
	v_addc_co_u32_e64 v242, s[66:67], 0, v242, s[66:67]
	v_addc_co_u32_e64 v242, s[68:69], 0, v242, s[68:69]
	v_addc_co_u32_e64 v242, s[70:71], 0, v242, s[70:71]
	v_addc_co_u32_e64 v242, s[72:73], 0, v242, s[72:73]
	v_addc_co_u32_e64 v242, s[74:75], 0, v242, s[74:75]
	v_cmp_ge_u32_e64 s[42:43], v216, vcc_lo
	v_cmp_ge_u32_e64 s[62:63], v214, vcc_lo
	v_cmp_ge_u32_e64 s[64:65], v213, vcc_lo
	v_cmp_ge_u32_e64 s[66:67], v212, vcc_lo
	v_cmp_ge_u32_e64 s[68:69], v211, vcc_lo
	v_cmp_ge_u32_e64 s[70:71], v210, vcc_lo
	v_cmp_ge_u32_e64 s[72:73], v207, vcc_lo
	v_cmp_ge_u32_e64 s[74:75], v194, vcc_lo
	v_addc_co_u32_e64 v242, s[42:43], 0, v242, s[42:43]
	v_addc_co_u32_e64 v242, s[62:63], 0, v242, s[62:63]
	v_addc_co_u32_e64 v242, s[64:65], 0, v242, s[64:65]
	v_addc_co_u32_e64 v242, s[66:67], 0, v242, s[66:67]
	v_addc_co_u32_e64 v242, s[68:69], 0, v242, s[68:69]
	v_addc_co_u32_e64 v242, s[70:71], 0, v242, s[70:71]
	v_addc_co_u32_e64 v242, s[72:73], 0, v242, s[72:73]
	v_addc_co_u32_e64 v242, s[74:75], 0, v242, s[74:75]
	v_cmp_ge_u32_e64 s[42:43], v195, vcc_lo
	v_cmp_ge_u32_e64 s[62:63], v193, vcc_lo
	v_cmp_ge_u32_e64 s[64:65], v192, vcc_lo
	v_cmp_ge_u32_e64 s[66:67], v191, vcc_lo
	v_cmp_ge_u32_e64 s[68:69], v190, vcc_lo
	v_cmp_ge_u32_e64 s[70:71], v189, vcc_lo
	v_cmp_ge_u32_e64 s[72:73], v188, vcc_lo
	v_cmp_ge_u32_e64 s[74:75], v186, vcc_lo
	v_addc_co_u32_e64 v242, s[42:43], 0, v242, s[42:43]
	v_addc_co_u32_e64 v242, s[62:63], 0, v242, s[62:63]
	v_addc_co_u32_e64 v242, s[64:65], 0, v242, s[64:65]
	v_addc_co_u32_e64 v242, s[66:67], 0, v242, s[66:67]
	v_addc_co_u32_e64 v242, s[68:69], 0, v242, s[68:69]
	v_addc_co_u32_e64 v242, s[70:71], 0, v242, s[70:71]
	v_addc_co_u32_e64 v242, s[72:73], 0, v242, s[72:73]
	v_addc_co_u32_e64 v242, s[74:75], 0, v242, s[74:75]
	s_nop 1
	v_add_u32_dpp v242, v242, v242 row_shr:1 row_mask:0xf bank_mask:0xf bound_ctrl:1
	s_nop 1
	v_add_u32_dpp v242, v242, v242 row_shr:2 row_mask:0xf bank_mask:0xf bound_ctrl:1
	s_nop 1
	v_add_u32_dpp v242, v242, v242 row_shr:4 row_mask:0xf bank_mask:0xf bound_ctrl:1
	s_nop 1
	v_add_u32_dpp v242, v242, v242 row_shr:8 row_mask:0xf bank_mask:0xf bound_ctrl:1
	s_nop 0
	v_readlane_b32 s42, v242, 15
	v_readlane_b32 s43, v242, 31
	s_add_i32 s42, s43, s42
	v_readlane_b32 s43, v242, 47
	s_add_i32 s42, s42, s43
	v_readlane_b32 s43, v242, 63
	s_add_i32 s42, s42, s43
	s_cmpk_gt_i32 s42, 0xff
	s_cselect_b32 s59, s42, s59
	s_cselect_b32 s101, vcc_lo, s101
	s_cmpk_eq_i32 s42, 0x100
	s_cbranch_scc1 .Lselq2_exit
	s_lshr_b32 vcc_hi, vcc_hi, 1
	s_cmp_lg_u32 vcc_hi, 0
	s_cbranch_scc1 .Lselq2_top

; template <int NB>
; __device__ __forceinline__ void bisect256(const unsigned (&x)[64], unsigned& tau_out, int& cge_out) {
;     ...
;     const unsigned cand = tau | (1u << bit);
;     unsigned cl = 0u;
; #pragma unroll
;     for (int blk = 0; blk < NB; ++blk) {
;       unsigned long long m0, m1, m2, m3, m4, m5, m6, m7;
;       asm volatile(
;           "v_cmp_ge_u32_e64 %1, %9, %17\n\tv_cmp_ge_u32_e64 %2, %10, %17\n\tv_cmp_ge_u32_e64 %3, %11, %17\n\tv_cmp_ge_u32_e64 %4, %12, %17\n\t"
;           "v_cmp_ge_u32_e64 %5, %13, %17\n\tv_cmp_ge_u32_e64 %6, %14, %17\n\tv_cmp_ge_u32_e64 %7, %15, %17\n\tv_cmp_ge_u32_e64 %8, %16, %17\n\t"
;           "v_addc_co_u32_e64 %0, %1, 0, %0, %1\n\tv_addc_co_u32_e64 %0, %2, 0, %0, %2\n\tv_addc_co_u32_e64 %0, %3, 0, %0, %3\n\t"
;           "v_addc_co_u32_e64 %0, %4, 0, %0, %4\n\tv_addc_co_u32_e64 %0, %5, 0, %0, %5\n\tv_addc_co_u32_e64 %0, %6, 0, %0, %6\n\t"
;           "v_addc_co_u32_e64 %0, %7, 0, %0, %7\n\tv_addc_co_u32_e64 %0, %8, 0, %0, %8"
;           : "+v"(cl), "=&s"(m0), "=&s"(m1), "=&s"(m2), "=&s"(m3), "=&s"(m4), "=&s"(m5), "=&s"(m6), "=&s"(m7)
;           : "v"(x[blk * 8 + 0]), "v"(x[blk * 8 + 1]), "v"(x[blk * 8 + 2]), "v"(x[blk * 8 + 3]), "v"(x[blk * 8 + 4]), "v"(x[blk * 8 + 5]),
;             "v"(x[blk * 8 + 6]), "v"(x[blk * 8 + 7]), "v"(cand));
;     }
;     cl += (unsigned)__builtin_amdgcn_update_dpp(0, (int)cl, 0x111, 0xf, 0xf, true);
;     cl += (unsigned)__builtin_amdgcn_update_dpp(0, (int)cl, 0x112, 0xf, 0xf, true);
;     cl += (unsigned)__builtin_amdgcn_update_dpp(0, (int)cl, 0x114, 0xf, 0xf, true);
;     cl += (unsigned)__builtin_amdgcn_update_dpp(0, (int)cl, 0x118, 0xf, 0xf, true);
;     const int cnt = __builtin_amdgcn_readlane((int)cl, 15) + __builtin_amdgcn_readlane((int)cl, 31) + __builtin_amdgcn_readlane((int)cl, 47) +
;                     __builtin_amdgcn_readlane((int)cl, 63);
;     if (cnt >= 256) { tau = cand; cge = cnt; }
;     if (cnt == 256) break;
;   }
.Lselq3_top:
	s_or_b32 vcc_lo, s101, vcc_hi
	v_cmp_ge_u32_e64 s[42:43], v239, vcc_lo
	v_cmp_ge_u32_e64 s[62:63], v238, vcc_lo
	v_cmp_ge_u32_e64 s[64:65], v237, vcc_lo
	v_cmp_ge_u32_e64 s[66:67], v236, vcc_lo
	v_cmp_ge_u32_e64 s[68:69], v235, vcc_lo
	v_cmp_ge_u32_e64 s[70:71], v234, vcc_lo
	v_cmp_ge_u32_e64 s[72:73], v233, vcc_lo
	v_cmp_ge_u32_e64 s[74:75], v231, vcc_lo
	v_addc_co_u32_e64 v242, s[42:43], 0, v17, s[42:43]
	v_addc_co_u32_e64 v242, s[62:63], 0, v242, s[62:63]
	v_addc_co_u32_e64 v242, s[64:65], 0, v242, s[64:65]
	v_addc_co_u32_e64 v242, s[66:67], 0, v242, s[66:67]
	v_addc_co_u32_e64 v242, s[68:69], 0, v242, s[68:69]
	v_addc_co_u32_e64 v242, s[70:71], 0, v242, s[70:71]
	v_addc_co_u32_e64 v242, s[72:73], 0, v242, s[72:73]
	v_addc_co_u32_e64 v242, s[74:75], 0, v242, s[74:75]
	v_cmp_ge_u32_e64 s[42:43], v232, vcc_lo
	v_cmp_ge_u32_e64 s[62:63], v230, vcc_lo
	v_cmp_ge_u32_e64 s[64:65], v229, vcc_lo
	v_cmp_ge_u32_e64 s[66:67], v228, vcc_lo
	v_cmp_ge_u32_e64 s[68:69], v227, vcc_lo
	v_cmp_ge_u32_e64 s[70:71], v226, vcc_lo
	v_cmp_ge_u32_e64 s[72:73], v225, vcc_lo
	v_cmp_ge_u32_e64 s[74:75], v223, vcc_lo
	v_addc_co_u32_e64 v242, s[42:43], 0, v242, s[42:43]
	v_addc_co_u32_e64 v242, s[62:63], 0, v242, s[62:63]
	v_addc_co_u32_e64 v242, s[64:65], 0, v242, s[64:65]
	v_addc_co_u32_e64 v242, s[66:67], 0, v242, s[66:67]
	v_addc_co_u32_e64 v242, s[68:69], 0, v242, s[68:69]
	v_addc_co_u32_e64 v242, s[70:71], 0, v242, s[70:71]
	v_addc_co_u32_e64 v242, s[72:73], 0, v242, s[72:73]
	v_addc_co_u32_e64 v242, s[74:75], 0, v242, s[74:75]
	v_cmp_ge_u32_e64 s[42:43], v224, vcc_lo
	v_cmp_ge_u32_e64 s[62:63], v222, vcc_lo
	v_cmp_ge_u32_e64 s[64:65], v221, vcc_lo
	v_cmp_ge_u32_e64 s[66:67], v220, vcc_lo
	v_cmp_ge_u32_e64 s[68:69], v219, vcc_lo
	v_cmp_ge_u32_e64 s[70:71], v218, vcc_lo
	v_cmp_ge_u32_e64 s[72:73], v217, vcc_lo
	v_cmp_ge_u32_e64 s[74:75], v215, vcc_lo
	v_addc_co_u32_e64 v242, s[42:43], 0, v242, s[42:43]
	v_addc_co_u32_e64 v242, s[62:63], 0, v242, s[62:63]
	v_addc_co_u32_e64 v242, s[64:65], 0, v242, s[64:65]
	v_addc_co_u32_e64 v242, s[66:67], 0, v242, s[66:67]
	v_addc_co_u32_e64 v242, s[68:69], 0, v242, s[68:69]
	v_addc_co_u32_e64 v242, s[70:71], 0, v242, s[70:71]
	v_addc_co_u32_e64 v242, s[72:73], 0, v242, s[72:73]
	v_addc_co_u32_e64 v242, s[74:75], 0, v242, s[74:75]
	v_cmp_ge_u32_e64 s[42:43], v216, vcc_lo
	v_cmp_ge_u32_e64 s[62:63], v214, vcc_lo
	v_cmp_ge_u32_e64 s[64:65], v213, vcc_lo
	v_cmp_ge_u32_e64 s[66:67], v212, vcc_lo
	v_cmp_ge_u32_e64 s[68:69], v211, vcc_lo
	v_cmp_ge_u32_e64 s[70:71], v210, vcc_lo
	v_cmp_ge_u32_e64 s[72:73], v207, vcc_lo
	v_cmp_ge_u32_e64 s[74:75], v194, vcc_lo
	v_addc_co_u32_e64 v242, s[42:43], 0, v242, s[42:43]
	v_addc_co_u32_e64 v242, s[62:63], 0, v242, s[62:63]
	v_addc_co_u32_e64 v242, s[64:65], 0, v242, s[64:65]
	v_addc_co_u32_e64 v242, s[66:67], 0, v242, s[66:67]
	v_addc_co_u32_e64 v242, s[68:69], 0, v242, s[68:69]
	v_addc_co_u32_e64 v242, s[70:71], 0, v242, s[70:71]
	v_addc_co_u32_e64 v242, s[72:73], 0, v242, s[72:73]
	v_addc_co_u32_e64 v242, s[74:75], 0, v242, s[74:75]
	s_nop 1
	v_add_u32_dpp v242, v242, v242 row_shr:1 row_mask:0xf bank_mask:0xf bound_ctrl:1
	s_nop 1
	v_add_u32_dpp v242, v242, v242 row_shr:2 row_mask:0xf bank_mask:0xf bound_ctrl:1
	s_nop 1
	v_add_u32_dpp v242, v242, v242 row_shr:4 row_mask:0xf bank_mask:0xf bound_ctrl:1
	s_nop 1
	v_add_u32_dpp v242, v242, v242 row_shr:8 row_mask:0xf bank_mask:0xf bound_ctrl:1
	s_nop 0
	v_readlane_b32 s42, v242, 15
	v_readlane_b32 s43, v242, 31
	s_add_i32 s42, s43, s42
	v_readlane_b32 s43, v242, 47
	s_add_i32 s42, s42, s43
	v_readlane_b32 s43, v242, 63
	s_add_i32 s42, s42, s43
	s_cmpk_gt_i32 s42, 0xff
	s_cselect_b32 s59, s42, s59
	s_cselect_b32 s101, vcc_lo, s101
	s_cmpk_eq_i32 s42, 0x100
	s_cbranch_scc1 .Lselq3_exit
	s_lshr_b32 vcc_hi, vcc_hi, 1
	s_cmp_lg_u32 vcc_hi, 0
	s_cbranch_scc1 .Lselq3_top

; template <int NB>
; __device__ __forceinline__ void bisect256(const unsigned (&x)[64], unsigned& tau_out, int& cge_out) {
;     ...
;     const unsigned cand = tau | (1u << bit);
;     unsigned cl = 0u;
; #pragma unroll
;     for (int blk = 0; blk < NB; ++blk) {
;       unsigned long long m0, m1, m2, m3, m4, m5, m6, m7;
;       asm volatile(
;           "v_cmp_ge_u32_e64 %1, %9, %17\n\tv_cmp_ge_u32_e64 %2, %10, %17\n\tv_cmp_ge_u32_e64 %3, %11, %17\n\tv_cmp_ge_u32_e64 %4, %12, %17\n\t"
;           "v_cmp_ge_u32_e64 %5, %13, %17\n\tv_cmp_ge_u32_e64 %6, %14, %17\n\tv_cmp_ge_u32_e64 %7, %15, %17\n\tv_cmp_ge_u32_e64 %8, %16, %17\n\t"
;           "v_addc_co_u32_e64 %0, %1, 0, %0, %1\n\tv_addc_co_u32_e64 %0, %2, 0, %0, %2\n\tv_addc_co_u32_e64 %0, %3, 0, %0, %3\n\t"
;           "v_addc_co_u32_e64 %0, %4, 0, %0, %4\n\tv_addc_co_u32_e64 %0, %5, 0, %0, %5\n\tv_addc_co_u32_e64 %0, %6, 0, %0, %6\n\t"
;           "v_addc_co_u32_e64 %0, %7, 0, %0, %7\n\tv_addc_co_u32_e64 %0, %8, 0, %0, %8"
;           : "+v"(cl), "=&s"(m0), "=&s"(m1), "=&s"(m2), "=&s"(m3), "=&s"(m4), "=&s"(m5), "=&s"(m6), "=&s"(m7)
;           : "v"(x[blk * 8 + 0]), "v"(x[blk * 8 + 1]), "v"(x[blk * 8 + 2]), "v"(x[blk * 8 + 3]), "v"(x[blk * 8 + 4]), "v"(x[blk * 8 + 5]),
;             "v"(x[blk * 8 + 6]), "v"(x[blk * 8 + 7]), "v"(cand));
;     }
;     cl += (unsigned)__builtin_amdgcn_update_dpp(0, (int)cl, 0x111, 0xf, 0xf, true);
;     cl += (unsigned)__builtin_amdgcn_update_dpp(0, (int)cl, 0x112, 0xf, 0xf, true);
;     cl += (unsigned)__builtin_amdgcn_update_dpp(0, (int)cl, 0x114, 0xf, 0xf, true);
;     cl += (unsigned)__builtin_amdgcn_update_dpp(0, (int)cl, 0x118, 0xf, 0xf, true);
;     const int cnt = __builtin_amdgcn_readlane((int)cl, 15) + __builtin_amdgcn_readlane((int)cl, 31) + __builtin_amdgcn_readlane((int)cl, 47) +
;                     __builtin_amdgcn_readlane((int)cl, 63);
;     if (cnt >= 256) { tau = cand; cge = cnt; }
;     if (cnt == 256) break;
;   }
.Lselq4_top:
	s_or_b32 vcc_lo, s101, vcc_hi
	v_cmp_ge_u32_e64 s[40:41], v239, vcc_lo
	v_cmp_ge_u32_e64 s[42:43], v238, vcc_lo
	v_cmp_ge_u32_e64 s[62:63], v237, vcc_lo
	v_cmp_ge_u32_e64 s[64:65], v236, vcc_lo
	v_cmp_ge_u32_e64 s[66:67], v235, vcc_lo
	v_cmp_ge_u32_e64 s[68:69], v234, vcc_lo
	v_cmp_ge_u32_e64 s[70:71], v233, vcc_lo
	v_cmp_ge_u32_e64 s[72:73], v231, vcc_lo
	v_addc_co_u32_e64 v242, s[40:41], 0, v17, s[40:41]
	v_addc_co_u32_e64 v242, s[42:43], 0, v242, s[42:43]
	v_addc_co_u32_e64 v242, s[62:63], 0, v242, s[62:63]
	v_addc_co_u32_e64 v242, s[64:65], 0, v242, s[64:65]
	v_addc_co_u32_e64 v242, s[66:67], 0, v242, s[66:67]
	v_addc_co_u32_e64 v242, s[68:69], 0, v242, s[68:69]
	v_addc_co_u32_e64 v242, s[70:71], 0, v242, s[70:71]
	v_addc_co_u32_e64 v242, s[72:73], 0, v242, s[72:73]
	v_cmp_ge_u32_e64 s[40:41], v232, vcc_lo
	v_cmp_ge_u32_e64 s[42:43], v230, vcc_lo
	v_cmp_ge_u32_e64 s[62:63], v229, vcc_lo
	v_cmp_ge_u32_e64 s[64:65], v228, vcc_lo
	v_cmp_ge_u32_e64 s[66:67], v227, vcc_lo
	v_cmp_ge_u32_e64 s[68:69], v226, vcc_lo
	v_cmp_ge_u32_e64 s[70:71], v225, vcc_lo
	v_cmp_ge_u32_e64 s[72:73], v223, vcc_lo
	v_addc_co_u32_e64 v242, s[40:41], 0, v242, s[40:41]
	v_addc_co_u32_e64 v242, s[42:43], 0, v242, s[42:43]
	v_addc_co_u32_e64 v242, s[62:63], 0, v242, s[62:63]
	v_addc_co_u32_e64 v242, s[64:65], 0, v242, s[64:65]
	v_addc_co_u32_e64 v242, s[66:67], 0, v242, s[66:67]
	v_addc_co_u32_e64 v242, s[68:69], 0, v242, s[68:69]
	v_addc_co_u32_e64 v242, s[70:71], 0, v242, s[70:71]
	v_addc_co_u32_e64 v242, s[72:73], 0, v242, s[72:73]
	v_cmp_ge_u32_e64 s[40:41], v224, vcc_lo
	v_cmp_ge_u32_e64 s[42:43], v222, vcc_lo
	v_cmp_ge_u32_e64 s[62:63], v221, vcc_lo
	v_cmp_ge_u32_e64 s[64:65], v220, vcc_lo
	v_cmp_ge_u32_e64 s[66:67], v219, vcc_lo
	v_cmp_ge_u32_e64 s[68:69], v218, vcc_lo
	v_cmp_ge_u32_e64 s[70:71], v217, vcc_lo
	v_cmp_ge_u32_e64 s[72:73], v215, vcc_lo
	v_addc_co_u32_e64 v242, s[40:41], 0, v242, s[40:41]
	v_addc_co_u32_e64 v242, s[42:43], 0, v242, s[42:43]
	v_addc_co_u32_e64 v242, s[62:63], 0, v242, s[62:63]
	v_addc_co_u32_e64 v242, s[64:65], 0, v242, s[64:65]
	v_addc_co_u32_e64 v242, s[66:67], 0, v242, s[66:67]
	v_addc_co_u32_e64 v242, s[68:69], 0, v242, s[68:69]
	v_addc_co_u32_e64 v242, s[70:71], 0, v242, s[70:71]
	v_addc_co_u32_e64 v242, s[72:73], 0, v242, s[72:73]
	s_nop 1
	v_add_u32_dpp v242, v242, v242 row_shr:1 row_mask:0xf bank_mask:0xf bound_ctrl:1
	s_nop 1
	v_add_u32_dpp v242, v242, v242 row_shr:2 row_mask:0xf bank_mask:0xf bound_ctrl:1
	s_nop 1
	v_add_u32_dpp v242, v242, v242 row_shr:4 row_mask:0xf bank_mask:0xf bound_ctrl:1
	s_nop 1
	v_add_u32_dpp v242, v242, v242 row_shr:8 row_mask:0xf bank_mask:0xf bound_ctrl:1
	s_nop 0
	v_readlane_b32 s40, v242, 15
	v_readlane_b32 s41, v242, 31
	s_add_i32 s40, s41, s40
	v_readlane_b32 s41, v242, 47
	s_add_i32 s40, s40, s41
	v_readlane_b32 s41, v242, 63
	s_add_i32 s40, s40, s41
	s_cmpk_gt_i32 s40, 0xff
	s_cselect_b32 s59, s40, s59
	s_cselect_b32 s101, vcc_lo, s101
	s_cmpk_eq_i32 s40, 0x100
	s_cbranch_scc1 .Lselq4_exit
	s_lshr_b32 vcc_hi, vcc_hi, 1
	s_cmp_lg_u32 vcc_hi, 0
	s_cbranch_scc1 .Lselq4_top

; template <int NB>
; __device__ __forceinline__ void bisect256(const unsigned (&x)[64], unsigned& tau_out, int& cge_out) {
;     ...
;     const unsigned cand = tau | (1u << bit);
;     unsigned cl = 0u;
; #pragma unroll
;     for (int blk = 0; blk < NB; ++blk) {
;       unsigned long long m0, m1, m2, m3, m4, m5, m6, m7;
;       asm volatile(
;           "v_cmp_ge_u32_e64 %1, %9, %17\n\tv_cmp_ge_u32_e64 %2, %10, %17\n\tv_cmp_ge_u32_e64 %3, %11, %17\n\tv_cmp_ge_u32_e64 %4, %12, %17\n\t"
;           "v_cmp_ge_u32_e64 %5, %13, %17\n\tv_cmp_ge_u32_e64 %6, %14, %17\n\tv_cmp_ge_u32_e64 %7, %15, %17\n\tv_cmp_ge_u32_e64 %8, %16, %17\n\t"
;           "v_addc_co_u32_e64 %0, %1, 0, %0, %1\n\tv_addc_co_u32_e64 %0, %2, 0, %0, %2\n\tv_addc_co_u32_e64 %0, %3, 0, %0, %3\n\t"
;           "v_addc_co_u32_e64 %0, %4, 0, %0, %4\n\tv_addc_co_u32_e64 %0, %5, 0, %0, %5\n\tv_addc_co_u32_e64 %0, %6, 0, %0, %6\n\t"
;           "v_addc_co_u32_e64 %0, %7, 0, %0, %7\n\tv_addc_co_u32_e64 %0, %8, 0, %0, %8"
;           : "+v"(cl), "=&s"(m0), "=&s"(m1), "=&s"(m2), "=&s"(m3), "=&s"(m4), "=&s"(m5), "=&s"(m6), "=&s"(m7)
;           : "v"(x[blk * 8 + 0]), "v"(x[blk * 8 + 1]), "v"(x[blk * 8 + 2]), "v"(x[blk * 8 + 3]), "v"(x[blk * 8 + 4]), "v"(x[blk * 8 + 5]),
;             "v"(x[blk * 8 + 6]), "v"(x[blk * 8 + 7]), "v"(cand));
;     }
;     cl += (unsigned)__builtin_amdgcn_update_dpp(0, (int)cl, 0x111, 0xf, 0xf, true);
;     cl += (unsigned)__builtin_amdgcn_update_dpp(0, (int)cl, 0x112, 0xf, 0xf, true);
;     cl += (unsigned)__builtin_amdgcn_update_dpp(0, (int)cl, 0x114, 0xf, 0xf, true);
;     cl += (unsigned)__builtin_amdgcn_update_dpp(0, (int)cl, 0x118, 0xf, 0xf, true);
;     const int cnt = __builtin_amdgcn_readlane((int)cl, 15) + __builtin_amdgcn_readlane((int)cl, 31) + __builtin_amdgcn_readlane((int)cl, 47) +
;                     __builtin_amdgcn_readlane((int)cl, 63);
;     if (cnt >= 256) { tau = cand; cge = cnt; }
;     if (cnt == 256) break;
;   }
.Lselq5_top:
	s_or_b32 vcc_lo, s101, vcc_hi
	v_cmp_ge_u32_e64 s[40:41], v239, vcc_lo
	v_cmp_ge_u32_e64 s[42:43], v238, vcc_lo
	v_cmp_ge_u32_e64 s[62:63], v237, vcc_lo
	v_cmp_ge_u32_e64 s[64:65], v236, vcc_lo
	v_cmp_ge_u32_e64 s[66:67], v235, vcc_lo
	v_cmp_ge_u32_e64 s[68:69], v234, vcc_lo
	v_cmp_ge_u32_e64 s[70:71], v233, vcc_lo
	v_cmp_ge_u32_e64 s[72:73], v231, vcc_lo
	v_addc_co_u32_e64 v242, s[40:41], 0, v17, s[40:41]
	v_addc_co_u32_e64 v242, s[42:43], 0, v242, s[42:43]
	v_addc_co_u32_e64 v242, s[62:63], 0, v242, s[62:63]
	v_addc_co_u32_e64 v242, s[64:65], 0, v242, s[64:65]
	v_addc_co_u32_e64 v242, s[66:67], 0, v242, s[66:67]
	v_addc_co_u32_e64 v242, s[68:69], 0, v242, s[68:69]
	v_addc_co_u32_e64 v242, s[70:71], 0, v242, s[70:71]
	v_addc_co_u32_e64 v242, s[72:73], 0, v242, s[72:73]
	v_cmp_ge_u32_e64 s[40:41], v232, vcc_lo
	v_cmp_ge_u32_e64 s[42:43], v230, vcc_lo
	v_cmp_ge_u32_e64 s[62:63], v229, vcc_lo
	v_cmp_ge_u32_e64 s[64:65], v228, vcc_lo
	v_cmp_ge_u32_e64 s[66:67], v227, vcc_lo
	v_cmp_ge_u32_e64 s[68:69], v226, vcc_lo
	v_cmp_ge_u32_e64 s[70:71], v225, vcc_lo
	v_cmp_ge_u32_e64 s[72:73], v223, vcc_lo
	v_addc_co_u32_e64 v242, s[40:41], 0, v242, s[40:41]
	v_addc_co_u32_e64 v242, s[42:43], 0, v242, s[42:43]
	v_addc_co_u32_e64 v242, s[62:63], 0, v242, s[62:63]
	v_addc_co_u32_e64 v242, s[64:65], 0, v242, s[64:65]
	v_addc_co_u32_e64 v242, s[66:67], 0, v242, s[66:67]
	v_addc_co_u32_e64 v242, s[68:69], 0, v242, s[68:69]
	v_addc_co_u32_e64 v242, s[70:71], 0, v242, s[70:71]
	v_addc_co_u32_e64 v242, s[72:73], 0, v242, s[72:73]
	s_nop 1
	v_add_u32_dpp v242, v242, v242 row_shr:1 row_mask:0xf bank_mask:0xf bound_ctrl:1
	s_nop 1
	v_add_u32_dpp v242, v242, v242 row_shr:2 row_mask:0xf bank_mask:0xf bound_ctrl:1
	s_nop 1
	v_add_u32_dpp v242, v242, v242 row_shr:4 row_mask:0xf bank_mask:0xf bound_ctrl:1
	s_nop 1
	v_add_u32_dpp v242, v242, v242 row_shr:8 row_mask:0xf bank_mask:0xf bound_ctrl:1
	s_nop 0
	v_readlane_b32 s40, v242, 15
	v_readlane_b32 s41, v242, 31
	s_add_i32 s40, s41, s40
	v_readlane_b32 s41, v242, 47
	s_add_i32 s40, s40, s41
	v_readlane_b32 s41, v242, 63
	s_add_i32 s40, s40, s41
	s_cmpk_gt_i32 s40, 0xff
	s_cselect_b32 s59, s40, s59
	s_cselect_b32 s101, vcc_lo, s101
	s_cmpk_eq_i32 s40, 0x100
	s_cbranch_scc1 .Lselq5_exit
	s_lshr_b32 vcc_hi, vcc_hi, 1
	s_cmp_lg_u32 vcc_hi, 0
	s_cbranch_scc1 .Lselq5_top

; template <int NB>
; __device__ __forceinline__ void bisect256(const unsigned (&x)[64], unsigned& tau_out, int& cge_out) {
;     ...
;     const unsigned cand = tau | (1u << bit);
;     unsigned cl = 0u;
; #pragma unroll
;     for (int blk = 0; blk < NB; ++blk) {
;       unsigned long long m0, m1, m2, m3, m4, m5, m6, m7;
;       asm volatile(
;           "v_cmp_ge_u32_e64 %1, %9, %17\n\tv_cmp_ge_u32_e64 %2, %10, %17\n\tv_cmp_ge_u32_e64 %3, %11, %17\n\tv_cmp_ge_u32_e64 %4, %12, %17\n\t"
;           "v_cmp_ge_u32_e64 %5, %13, %17\n\tv_cmp_ge_u32_e64 %6, %14, %17\n\tv_cmp_ge_u32_e64 %7, %15, %17\n\tv_cmp_ge_u32_e64 %8, %16, %17\n\t"
;           "v_addc_co_u32_e64 %0, %1, 0, %0, %1\n\tv_addc_co_u32_e64 %0, %2, 0, %0, %2\n\tv_addc_co_u32_e64 %0, %3, 0, %0, %3\n\t"
;           "v_addc_co_u32_e64 %0, %4, 0, %0, %4\n\tv_addc_co_u32_e64 %0, %5, 0, %0, %5\n\tv_addc_co_u32_e64 %0, %6, 0, %0, %6\n\t"
;           "v_addc_co_u32_e64 %0, %7, 0, %0, %7\n\tv_addc_co_u32_e64 %0, %8, 0, %0, %8"
;           : "+v"(cl), "=&s"(m0), "=&s"(m1), "=&s"(m2), "=&s"(m3), "=&s"(m4), "=&s"(m5), "=&s"(m6), "=&s"(m7)
;           : "v"(x[blk * 8 + 0]), "v"(x[blk * 8 + 1]), "v"(x[blk * 8 + 2]), "v"(x[blk * 8 + 3]), "v"(x[blk * 8 + 4]), "v"(x[blk * 8 + 5]),
;             "v"(x[blk * 8 + 6]), "v"(x[blk * 8 + 7]), "v"(cand));
;     }
;     cl += (unsigned)__builtin_amdgcn_update_dpp(0, (int)cl, 0x111, 0xf, 0xf, true);
;     cl += (unsigned)__builtin_amdgcn_update_dpp(0, (int)cl, 0x112, 0xf, 0xf, true);
;     cl += (unsigned)__builtin_amdgcn_update_dpp(0, (int)cl, 0x114, 0xf, 0xf, true);
;     cl += (unsigned)__builtin_amdgcn_update_dpp(0, (int)cl, 0x118, 0xf, 0xf, true);
;     const int cnt = __builtin_amdgcn_readlane((int)cl, 15) + __builtin_amdgcn_readlane((int)cl, 31) + __builtin_amdgcn_readlane((int)cl, 47) +
;                     __builtin_amdgcn_readlane((int)cl, 63);
;     if (cnt >= 256) { tau = cand; cge = cnt; }
;     if (cnt == 256) break;
;   }
.Lselq6_top:
	s_or_b32 vcc_lo, s101, vcc_hi
	v_cmp_ge_u32_e64 s[0:1], v239, vcc_lo
	v_cmp_ge_u32_e64 s[2:3], v238, vcc_lo
	v_cmp_ge_u32_e64 s[4:5], v237, vcc_lo
	v_cmp_ge_u32_e64 s[6:7], v236, vcc_lo
	v_cmp_ge_u32_e64 s[8:9], v235, vcc_lo
	v_cmp_ge_u32_e64 s[10:11], v234, vcc_lo
	v_cmp_ge_u32_e64 s[12:13], v233, vcc_lo
	v_cmp_ge_u32_e64 s[14:15], v231, vcc_lo
	v_addc_co_u32_e64 v166, s[0:1], 0, v17, s[0:1]
	v_addc_co_u32_e64 v166, s[2:3], 0, v166, s[2:3]
	v_addc_co_u32_e64 v166, s[4:5], 0, v166, s[4:5]
	v_addc_co_u32_e64 v166, s[6:7], 0, v166, s[6:7]
	v_addc_co_u32_e64 v166, s[8:9], 0, v166, s[8:9]
	v_addc_co_u32_e64 v166, s[10:11], 0, v166, s[10:11]
	v_addc_co_u32_e64 v166, s[12:13], 0, v166, s[12:13]
	v_addc_co_u32_e64 v166, s[14:15], 0, v166, s[14:15]
	v_cmp_ge_u32_e64 s[0:1], v232, vcc_lo
	v_cmp_ge_u32_e64 s[2:3], v230, vcc_lo
	v_cmp_ge_u32_e64 s[4:5], v229, vcc_lo
	v_cmp_ge_u32_e64 s[6:7], v228, vcc_lo
	v_cmp_ge_u32_e64 s[8:9], v227, vcc_lo
	v_cmp_ge_u32_e64 s[10:11], v226, vcc_lo
	v_cmp_ge_u32_e64 s[12:13], v225, vcc_lo
	v_cmp_ge_u32_e64 s[14:15], v223, vcc_lo
	v_addc_co_u32_e64 v166, s[0:1], 0, v166, s[0:1]
	v_addc_co_u32_e64 v166, s[2:3], 0, v166, s[2:3]
	v_addc_co_u32_e64 v166, s[4:5], 0, v166, s[4:5]
	v_addc_co_u32_e64 v166, s[6:7], 0, v166, s[6:7]
	v_addc_co_u32_e64 v166, s[8:9], 0, v166, s[8:9]
	v_addc_co_u32_e64 v166, s[10:11], 0, v166, s[10:11]
	v_addc_co_u32_e64 v166, s[12:13], 0, v166, s[12:13]
	v_addc_co_u32_e64 v166, s[14:15], 0, v166, s[14:15]
	v_cmp_ge_u32_e64 s[0:1], v224, vcc_lo
	v_cmp_ge_u32_e64 s[2:3], v222, vcc_lo
	v_cmp_ge_u32_e64 s[4:5], v221, vcc_lo
	v_cmp_ge_u32_e64 s[6:7], v220, vcc_lo
	v_cmp_ge_u32_e64 s[8:9], v219, vcc_lo
	v_cmp_ge_u32_e64 s[10:11], v218, vcc_lo
	v_cmp_ge_u32_e64 s[12:13], v217, vcc_lo
	v_cmp_ge_u32_e64 s[14:15], v215, vcc_lo
	v_addc_co_u32_e64 v166, s[0:1], 0, v166, s[0:1]
	v_addc_co_u32_e64 v166, s[2:3], 0, v166, s[2:3]
	v_addc_co_u32_e64 v166, s[4:5], 0, v166, s[4:5]
	v_addc_co_u32_e64 v166, s[6:7], 0, v166, s[6:7]
	v_addc_co_u32_e64 v166, s[8:9], 0, v166, s[8:9]
	v_addc_co_u32_e64 v166, s[10:11], 0, v166, s[10:11]
	v_addc_co_u32_e64 v166, s[12:13], 0, v166, s[12:13]
	v_addc_co_u32_e64 v166, s[14:15], 0, v166, s[14:15]
	v_cmp_ge_u32_e64 s[0:1], v216, vcc_lo
	v_cmp_ge_u32_e64 s[2:3], v214, vcc_lo
	v_cmp_ge_u32_e64 s[4:5], v213, vcc_lo
	v_cmp_ge_u32_e64 s[6:7], v212, vcc_lo
	v_cmp_ge_u32_e64 s[8:9], v211, vcc_lo
	v_cmp_ge_u32_e64 s[10:11], v210, vcc_lo
	v_cmp_ge_u32_e64 s[12:13], v207, vcc_lo
	v_cmp_ge_u32_e64 s[14:15], v194, vcc_lo
	v_addc_co_u32_e64 v166, s[0:1], 0, v166, s[0:1]
	v_addc_co_u32_e64 v166, s[2:3], 0, v166, s[2:3]
	v_addc_co_u32_e64 v166, s[4:5], 0, v166, s[4:5]
	v_addc_co_u32_e64 v166, s[6:7], 0, v166, s[6:7]
	v_addc_co_u32_e64 v166, s[8:9], 0, v166, s[8:9]
	v_addc_co_u32_e64 v166, s[10:11], 0, v166, s[10:11]
	v_addc_co_u32_e64 v166, s[12:13], 0, v166, s[12:13]
	v_addc_co_u32_e64 v166, s[14:15], 0, v166, s[14:15]
	v_cmp_ge_u32_e64 s[0:1], v195, vcc_lo
	v_cmp_ge_u32_e64 s[2:3], v193, vcc_lo
	v_cmp_ge_u32_e64 s[4:5], v192, vcc_lo
	v_cmp_ge_u32_e64 s[6:7], v191, vcc_lo
	v_cmp_ge_u32_e64 s[8:9], v190, vcc_lo
	v_cmp_ge_u32_e64 s[10:11], v189, vcc_lo
	v_cmp_ge_u32_e64 s[12:13], v188, vcc_lo
	v_cmp_ge_u32_e64 s[14:15], v186, vcc_lo
	v_addc_co_u32_e64 v166, s[0:1], 0, v166, s[0:1]
	v_addc_co_u32_e64 v166, s[2:3], 0, v166, s[2:3]
	v_addc_co_u32_e64 v166, s[4:5], 0, v166, s[4:5]
	v_addc_co_u32_e64 v166, s[6:7], 0, v166, s[6:7]
	v_addc_co_u32_e64 v166, s[8:9], 0, v166, s[8:9]
	v_addc_co_u32_e64 v166, s[10:11], 0, v166, s[10:11]
	v_addc_co_u32_e64 v166, s[12:13], 0, v166, s[12:13]
	v_addc_co_u32_e64 v166, s[14:15], 0, v166, s[14:15]
	v_cmp_ge_u32_e64 s[0:1], v187, vcc_lo
	v_cmp_ge_u32_e64 s[2:3], v185, vcc_lo
	v_cmp_ge_u32_e64 s[4:5], v184, vcc_lo
	v_cmp_ge_u32_e64 s[6:7], v183, vcc_lo
	v_cmp_ge_u32_e64 s[8:9], v182, vcc_lo
	v_cmp_ge_u32_e64 s[10:11], v181, vcc_lo
	v_cmp_ge_u32_e64 s[12:13], v180, vcc_lo
	v_cmp_ge_u32_e64 s[14:15], v178, vcc_lo
	v_addc_co_u32_e64 v166, s[0:1], 0, v166, s[0:1]
	v_addc_co_u32_e64 v166, s[2:3], 0, v166, s[2:3]
	v_addc_co_u32_e64 v166, s[4:5], 0, v166, s[4:5]
	v_addc_co_u32_e64 v166, s[6:7], 0, v166, s[6:7]
	v_addc_co_u32_e64 v166, s[8:9], 0, v166, s[8:9]
	v_addc_co_u32_e64 v166, s[10:11], 0, v166, s[10:11]
	v_addc_co_u32_e64 v166, s[12:13], 0, v166, s[12:13]
	v_addc_co_u32_e64 v166, s[14:15], 0, v166, s[14:15]
	v_cmp_ge_u32_e64 s[0:1], v179, vcc_lo
	v_cmp_ge_u32_e64 s[2:3], v177, vcc_lo
	v_cmp_ge_u32_e64 s[4:5], v176, vcc_lo
	v_cmp_ge_u32_e64 s[6:7], v175, vcc_lo
	v_cmp_ge_u32_e64 s[8:9], v174, vcc_lo
	v_cmp_ge_u32_e64 s[10:11], v173, vcc_lo
	v_cmp_ge_u32_e64 s[12:13], v172, vcc_lo
	v_cmp_ge_u32_e64 s[14:15], v115, vcc_lo
	v_addc_co_u32_e64 v166, s[0:1], 0, v166, s[0:1]
	v_addc_co_u32_e64 v166, s[2:3], 0, v166, s[2:3]
	v_addc_co_u32_e64 v166, s[4:5], 0, v166, s[4:5]
	v_addc_co_u32_e64 v166, s[6:7], 0, v166, s[6:7]
	v_addc_co_u32_e64 v166, s[8:9], 0, v166, s[8:9]
	v_addc_co_u32_e64 v166, s[10:11], 0, v166, s[10:11]
	v_addc_co_u32_e64 v166, s[12:13], 0, v166, s[12:13]
	v_addc_co_u32_e64 v166, s[14:15], 0, v166, s[14:15]
	v_cmp_ge_u32_e64 s[0:1], v243, vcc_lo
	v_cmp_ge_u32_e64 s[2:3], v242, vcc_lo
	v_cmp_ge_u32_e64 s[4:5], v241, vcc_lo
	v_cmp_ge_u32_e64 s[6:7], v240, vcc_lo
	v_cmp_ge_u32_e64 s[8:9], v171, vcc_lo
	v_cmp_ge_u32_e64 s[10:11], v170, vcc_lo
	v_cmp_ge_u32_e64 s[12:13], v169, vcc_lo
	v_cmp_ge_u32_e64 s[14:15], v168, vcc_lo
	v_addc_co_u32_e64 v166, s[0:1], 0, v166, s[0:1]
	v_addc_co_u32_e64 v166, s[2:3], 0, v166, s[2:3]
	v_addc_co_u32_e64 v166, s[4:5], 0, v166, s[4:5]
	v_addc_co_u32_e64 v166, s[6:7], 0, v166, s[6:7]
	v_addc_co_u32_e64 v166, s[8:9], 0, v166, s[8:9]
	v_addc_co_u32_e64 v166, s[10:11], 0, v166, s[10:11]
	v_addc_co_u32_e64 v166, s[12:13], 0, v166, s[12:13]
	v_addc_co_u32_e64 v166, s[14:15], 0, v166, s[14:15]
	s_nop 1
	v_add_u32_dpp v166, v166, v166 row_shr:1 row_mask:0xf bank_mask:0xf bound_ctrl:1
	s_nop 1
	v_add_u32_dpp v166, v166, v166 row_shr:2 row_mask:0xf bank_mask:0xf bound_ctrl:1
	s_nop 1
	v_add_u32_dpp v166, v166, v166 row_shr:4 row_mask:0xf bank_mask:0xf bound_ctrl:1
	s_nop 1
	v_add_u32_dpp v166, v166, v166 row_shr:8 row_mask:0xf bank_mask:0xf bound_ctrl:1
	s_nop 0
	v_readlane_b32 s0, v166, 15
	v_readlane_b32 s1, v166, 31
	s_add_i32 s0, s1, s0
	v_readlane_b32 s1, v166, 47
	s_add_i32 s0, s0, s1
	v_readlane_b32 s1, v166, 63
	s_add_i32 s0, s0, s1
	s_cmpk_gt_i32 s0, 0xff
	s_cselect_b32 s59, s0, s59
	s_cselect_b32 s101, vcc_lo, s101
	s_cmpk_eq_i32 s0, 0x100
	s_cbranch_scc1 .Lselq6_exit
	s_lshr_b32 vcc_hi, vcc_hi, 1
	s_cmp_lg_u32 vcc_hi, 0
	s_cbranch_scc1 .Lselq6_top

; template <int NB>
; __device__ __forceinline__ void bisect256(const unsigned (&x)[64], unsigned& tau_out, int& cge_out) {
;     ...
;     const unsigned cand = tau | (1u << bit);
;     unsigned cl = 0u;
; #pragma unroll
;     for (int blk = 0; blk < NB; ++blk) {
;       unsigned long long m0, m1, m2, m3, m4, m5, m6, m7;
;       asm volatile(
;           "v_cmp_ge_u32_e64 %1, %9, %17\n\tv_cmp_ge_u32_e64 %2, %10, %17\n\tv_cmp_ge_u32_e64 %3, %11, %17\n\tv_cmp_ge_u32_e64 %4, %12, %17\n\t"
;           "v_cmp_ge_u32_e64 %5, %13, %17\n\tv_cmp_ge_u32_e64 %6, %14, %17\n\tv_cmp_ge_u32_e64 %7, %15, %17\n\tv_cmp_ge_u32_e64 %8, %16, %17\n\t"
;           "v_addc_co_u32_e64 %0, %1, 0, %0, %1\n\tv_addc_co_u32_e64 %0, %2, 0, %0, %2\n\tv_addc_co_u32_e64 %0, %3, 0, %0, %3\n\t"
;           "v_addc_co_u32_e64 %0, %4, 0, %0, %4\n\tv_addc_co_u32_e64 %0, %5, 0, %0, %5\n\tv_addc_co_u32_e64 %0, %6, 0, %0, %6\n\t"
;           "v_addc_co_u32_e64 %0, %7, 0, %0, %7\n\tv_addc_co_u32_e64 %0, %8, 0, %0, %8"
;           : "+v"(cl), "=&s"(m0), "=&s"(m1), "=&s"(m2), "=&s"(m3), "=&s"(m4), "=&s"(m5), "=&s"(m6), "=&s"(m7)
;           : "v"(x[blk * 8 + 0]), "v"(x[blk * 8 + 1]), "v"(x[blk * 8 + 2]), "v"(x[blk * 8 + 3]), "v"(x[blk * 8 + 4]), "v"(x[blk * 8 + 5]),
;             "v"(x[blk * 8 + 6]), "v"(x[blk * 8 + 7]), "v"(cand));
;     }
;     cl += (unsigned)__builtin_amdgcn_update_dpp(0, (int)cl, 0x111, 0xf, 0xf, true);
;     cl += (unsigned)__builtin_amdgcn_update_dpp(0, (int)cl, 0x112, 0xf, 0xf, true);
;     cl += (unsigned)__builtin_amdgcn_update_dpp(0, (int)cl, 0x114, 0xf, 0xf, true);
;     cl += (unsigned)__builtin_amdgcn_update_dpp(0, (int)cl, 0x118, 0xf, 0xf, true);
;     const int cnt = __builtin_amdgcn_readlane((int)cl, 15) + __builtin_amdgcn_readlane((int)cl, 31) + __builtin_amdgcn_readlane((int)cl, 47) +
;                     __builtin_amdgcn_readlane((int)cl, 63);
;     if (cnt >= 256) { tau = cand; cge = cnt; }
;     if (cnt == 256) break;
;   }
.Lselq7_top:
	s_or_b32 vcc_lo, s101, vcc_hi
	v_cmp_ge_u32_e64 s[0:1], v239, vcc_lo
	v_cmp_ge_u32_e64 s[2:3], v238, vcc_lo
	v_cmp_ge_u32_e64 s[4:5], v237, vcc_lo
	v_cmp_ge_u32_e64 s[6:7], v236, vcc_lo
	v_cmp_ge_u32_e64 s[8:9], v235, vcc_lo
	v_cmp_ge_u32_e64 s[10:11], v234, vcc_lo
	v_cmp_ge_u32_e64 s[12:13], v233, vcc_lo
	v_cmp_ge_u32_e64 s[14:15], v231, vcc_lo
	v_addc_co_u32_e64 v166, s[0:1], 0, v17, s[0:1]
	v_addc_co_u32_e64 v166, s[2:3], 0, v166, s[2:3]
	v_addc_co_u32_e64 v166, s[4:5], 0, v166, s[4:5]
	v_addc_co_u32_e64 v166, s[6:7], 0, v166, s[6:7]
	v_addc_co_u32_e64 v166, s[8:9], 0, v166, s[8:9]
	v_addc_co_u32_e64 v166, s[10:11], 0, v166, s[10:11]
	v_addc_co_u32_e64 v166, s[12:13], 0, v166, s[12:13]
	v_addc_co_u32_e64 v166, s[14:15], 0, v166, s[14:15]
	s_nop 1
	v_add_u32_dpp v166, v166, v166 row_shr:1 row_mask:0xf bank_mask:0xf bound_ctrl:1
	s_nop 1
	v_add_u32_dpp v166, v166, v166 row_shr:2 row_mask:0xf bank_mask:0xf bound_ctrl:1
	s_nop 1
	v_add_u32_dpp v166, v166, v166 row_shr:4 row_mask:0xf bank_mask:0xf bound_ctrl:1
	s_nop 1
	v_add_u32_dpp v166, v166, v166 row_shr:8 row_mask:0xf bank_mask:0xf bound_ctrl:1
	s_nop 0
	v_readlane_b32 s0, v166, 15
	v_readlane_b32 s1, v166, 31
	s_add_i32 s0, s1, s0
	v_readlane_b32 s1, v166, 47
	s_add_i32 s0, s0, s1
	v_readlane_b32 s1, v166, 63
	s_add_i32 s0, s0, s1
	s_cmpk_gt_i32 s0, 0xff
	s_cselect_b32 s59, s0, s59
	s_cselect_b32 s101, vcc_lo, s101
	s_cmpk_eq_i32 s0, 0x100
	s_cbranch_scc1 .Lselq7_exit
	s_lshr_b32 vcc_hi, vcc_hi, 1
	s_cmp_lg_u32 vcc_hi, 0
	s_cbranch_scc1 .Lselq7_top
